# cand2 shifted by 3 s_nop at entry (code placement check)
# speedup vs baseline: 1.0018x; 1.0018x over previous
; #define LAS __attribute__((address_space(3)))
; __global__ void __launch_bounds__(NWAVES * 64, 2) skel_fwd(Args args) {
;     ...
;     F.lds = (LAS unsigned char*)lds;
;     F.MISC = (volatile LAS unsigned*)(F.lds + MISC_OFF);
;     F.tid = threadIdx.x; F.lane = F.tid & 63; F.wave = __builtin_amdgcn_readfirstlane(F.tid >> 6);
;     F.G = gridDim.x; { const int bx = blockIdx.x; F.vcu = (F.G % 8 == 0) ? (bx % 8) * (F.G / 8) + bx / 8 : bx; }
_Z8skel_fwd4Args:
	s_nop 0
	s_nop 0
	s_nop 0
	s_load_dword s76, s[0:1], 0x98
	s_mov_b32 s73, s2
	s_add_u32 s2, s0, 0x98
	s_addc_u32 s3, s1, 0
	s_mov_b32 s78, s73
	v_writelane_b32 v243, s2, 0
	s_nop 1
	v_writelane_b32 v243, s3, 1
	s_waitcnt lgkmcnt(0)
	s_and_b32 s2, s76, 7
	s_cmp_lg_u32 s2, 0
	s_cbranch_scc1 .LBB0_2
	s_ashr_i32 s3, s73, 31
	s_lshr_b32 s3, s3, 29
	s_add_i32 s3, s73, s3
	s_and_b32 s4, s3, -8
	s_ashr_i32 s2, s76, 3
	s_sub_i32 s4, s73, s4
	s_mul_i32 s2, s2, s4
	s_ashr_i32 s3, s3, 3
	s_add_i32 s78, s2, s3
